# speedup vs baseline: 1.0173x; 1.0030x over previous
; #define SCHED() __builtin_amdgcn_sched_barrier(0)
; #define DSR(dst, addr, off) asm volatile("ds_read_b128 %0, %1 offset:%2" : "=&v"(dst) : "v"(addr), "n"(off) : "memory")
; #define LGKM(n) asm volatile("s_waitcnt lgkmcnt(%0)" ::"n"(n) : "memory")
; #define DSR(dst, addr, off) asm volatile("ds_read_b128 %0, %1 offset:%2" : "=&v"(dst) : "v"(addr), "n"(off) : "memory")
; #define LGKM(n) asm volatile("s_waitcnt lgkmcnt(%0)" ::"n"(n) : "memory")
; __device__ __forceinline__ void attn_phase(char* shm, const Params& p, const u16* __restrict__ qb, const u16* __restrict__ kb,
;                                            const u16* __restrict__ vT, u16* __restrict__ attn) {
;     ...
;         const float df = (float)(kt * 64 + u * 32 + 4 * hh - qpos);
;         bf16x8 P[2][2];
;         bf16x8 kf[2], qf[2];
;         DSR(kf[0], kb_ + kL0, u * 8192); DSR(qf[0], qaddr, 0);
; #pragma unroll
;         for (int c = 0; c < 2; ++c) {
;           f32x16 Sx;
; #pragma unroll
;           for (int i = 0; i < 16; ++i) Sx[i] = -sl2 * fabsf(df + (float)((i & 3) + 8 * (i >> 2)));
; #pragma unroll
;           for (int ks = 0; ks < 4; ++ks) {
;             const int f = c * 4 + ks;
;             if (f < 7) {
;               DSR(kf[(f + 1) & 1], kb_ + (kL0 ^ ((((f + 1) >> 2) * 8 + ((f + 1) & 3) * 2) << 4)), u * 8192);
;               DSR(qf[(f + 1) & 1], qaddr, (f + 1) * 1024);
;               LGKM(2);
;             } else LGKM(0);
;             SCHED();
;             Sx = __builtin_amdgcn_mfma_f32_32x32x16_bf16(kf[f & 1], qf[f & 1], Sx, 0, 0, 0);
;             SCHED();
;           }
;           float pv[16];
; #pragma unroll
;           for (int i = 0; i < 16; ++i) { pv[i] = __builtin_amdgcn_exp2f(Sx[i]); lsum[c] += pv[i]; }
.LBB0_299:
	v_cvt_f32_i32_e32 v128, v205
	v_add_u32_e32 v160, s44, v188
	ds_read_b128 v[206:209], v160 offset:0
	ds_read_b128 v[210:213], v185 offset:0
	v_add_u32_e32 v214, s44, v190
	ds_read_b128 v[218:221], v214 offset:0
	ds_read_b128 v[222:225], v185 offset:0x400
	v_add_u32_e32 v215, s44, v191
	ds_read_b128 v[242:245], v215 offset:0
	ds_read_b128 v[246:249], v185 offset:0x800
	v_add_f32_e32 v129, 1.0, v128
	v_add_f32_e64 v130, v128, s12
	v_add_f32_e64 v131, v128, s13
	v_add_f32_e64 v132, v128, s14
	v_add_f32_e64 v133, v128, s15
	v_add_f32_e64 v134, v128, s20
	v_add_f32_e64 v135, v128, s21
	v_add_f32_e64 v136, v128, s22
	v_add_f32_e64 v137, v128, s23
	v_add_f32_e64 v138, v128, s24
	v_add_f32_e64 v139, v128, s25
	v_add_f32_e64 v140, v128, s26
	v_add_f32_e64 v141, v128, s27
	v_add_f32_e64 v142, v128, s28
	v_add_f32_e64 v143, v128, s29
	s_add_i32 s0, s44, 0x4000
	v_mul_f32_e64 v142, v178, |v142|
	v_mul_f32_e64 v143, v179, |v143|
	v_mul_f32_e64 v140, v178, |v140|
	v_mul_f32_e64 v141, v179, |v141|
	v_mul_f32_e64 v138, v178, |v138|
	v_mul_f32_e64 v139, v179, |v139|
	v_mul_f32_e64 v136, v178, |v136|
	v_mul_f32_e64 v137, v179, |v137|
	v_mul_f32_e64 v134, v178, |v134|
	v_mul_f32_e64 v135, v179, |v135|
	v_mul_f32_e64 v132, v178, |v132|
	v_mul_f32_e64 v133, v179, |v133|
	v_mul_f32_e64 v130, v178, |v130|
	v_mul_f32_e64 v131, v179, |v131|
	v_mul_f32_e64 v128, v170, |v128|
	v_mul_f32_e64 v129, v171, |v129|
	s_nop 1
	s_waitcnt lgkmcnt(4)
	v_readfirstlane_b32 s88, v128
	s_cmp_gt_u32 s88, 0xc35c0000
	s_cselect_b32 s89, 1, 0
	s_mov_b32 s90, 0
	v_mfma_f32_32x32x16_bf16 v[144:159], v[206:209], v[210:213], v[128:143]
	v_add_u32_e32 v226, s44, v192
	ds_read_b128 v[206:209], v226 offset:0
	ds_read_b128 v[210:213], v185 offset:0xc00
	s_waitcnt lgkmcnt(4)
	v_mfma_f32_32x32x16_bf16 v[144:159], v[218:221], v[222:225], v[144:159]
	v_add_u32_e32 v227, s44, v193
	ds_read_b128 v[218:221], v227 offset:0
	ds_read_b128 v[222:225], v185 offset:0x1000
	s_waitcnt lgkmcnt(4)
	v_mfma_f32_32x32x16_bf16 v[144:159], v[242:245], v[246:249], v[144:159]
	v_add_u32_e32 v229, s44, v194
	ds_read_b128 v[242:245], v229 offset:0
	ds_read_b128 v[246:249], v185 offset:0x1400
	s_waitcnt lgkmcnt(4)
	v_mfma_f32_32x32x16_bf16 v[144:159], v[206:209], v[210:213], v[144:159]
	v_add_u32_e32 v230, s44, v195
	ds_read_b128 v[206:209], v230 offset:0
	ds_read_b128 v[210:213], v185 offset:0x1800
	s_waitcnt lgkmcnt(4)
	v_mfma_f32_32x32x16_bf16 v[128:143], v[218:221], v[222:225], v[128:143]
	v_add_u32_e32 v232, s44, v196
	ds_read_b128 v[218:221], v232 offset:0
	ds_read_b128 v[222:225], v185 offset:0x1c00
	s_waitcnt lgkmcnt(4)
	v_mfma_f32_32x32x16_bf16 v[128:143], v[242:245], v[246:249], v[128:143]
	s_waitcnt lgkmcnt(2)
	v_mfma_f32_32x32x16_bf16 v[128:143], v[206:209], v[210:213], v[128:143]
	s_waitcnt lgkmcnt(0)
	v_mfma_f32_32x32x16_bf16 v[128:143], v[218:221], v[222:225], v[128:143]
	s_nop 3
	s_cmp_eq_u32 s89, 0
	s_cbranch_scc1 .Lattn_exp_normal_0_0
	v_max3_f32 v240, v144, v145, v146
	v_max3_f32 v240, v240, v147, v148
	v_max3_f32 v240, v240, v149, v150
	v_max3_f32 v240, v240, v151, v152
	v_max3_f32 v240, v240, v153, v154
	v_max3_f32 v240, v240, v155, v156
	v_max3_f32 v240, v240, v157, v158
	v_max_f32_e32 v240, v240, v159
	v_cmp_ngt_f32_e32 vcc, 0xc3180000, v240
	s_and_b64 vcc, exec, vcc
	s_cbranch_vccnz .Lattn_exp_normal_0_0
	v_mov_b32_e32 v144, 0
	v_mov_b32_e32 v145, 0
	v_mov_b32_e32 v146, 0
	v_mov_b32_e32 v147, 0
	v_mov_b32_e32 v148, 0
	v_mov_b32_e32 v149, 0
	v_mov_b32_e32 v150, 0
	v_mov_b32_e32 v151, 0
	s_add_i32 s90, s90, 1
	s_branch .Lattn_exp_done_0_0

; #define DSR(dst, addr, off) asm volatile("ds_read_b128 %0, %1 offset:%2" : "=&v"(dst) : "v"(addr), "n"(off) : "memory")
; #define DSR(dst, addr, off) asm volatile("ds_read_b128 %0, %1 offset:%2" : "=&v"(dst) : "v"(addr), "n"(off) : "memory")
; __device__ __forceinline__ void attn_phase(char* shm, const Params& p, const u16* __restrict__ qb, const u16* __restrict__ kb,
;                                            const u16* __restrict__ vT, u16* __restrict__ attn) {
;     ...
;           float pv[16];
; #pragma unroll
;           for (int i = 0; i < 16; ++i) { pv[i] = __builtin_amdgcn_exp2f(Sx[i]); lsum[c] += pv[i]; }
; #pragma unroll
;           for (int a = 0; a < 2; ++a) {
;             i32x4 t4;
; #pragma unroll
;             for (int i = 0; i < 4; ++i) t4[i] = pk_bf16(pv[a * 8 + 2 * i], pv[a * 8 + 2 * i + 1]);
;             P[c][a] = __builtin_bit_cast(bf16x8, t4);
;           }
;         }
;         bf16x8 vf[2];
;         DSR(vf[0], vb_ + (vM0 ^ ((u * 4) << 4)), 0);
.Lattn_exp_done_0_0:
	s_nop 3
	s_cmp_eq_u32 s89, 0
	s_cbranch_scc1 .Lattn_exp_normal_0_1
	v_max3_f32 v240, v128, v129, v130
	v_max3_f32 v240, v240, v131, v132
	v_max3_f32 v240, v240, v133, v134
	v_max3_f32 v240, v240, v135, v136
	v_max3_f32 v240, v240, v137, v138
	v_max3_f32 v240, v240, v139, v140
	v_max3_f32 v240, v240, v141, v142
	v_max_f32_e32 v240, v240, v143
	v_cmp_ngt_f32_e32 vcc, 0xc3180000, v240
	s_and_b64 vcc, exec, vcc
	s_cbranch_vccnz .Lattn_exp_normal_0_1
	v_add_u32_e32 v152, s0, v189
	ds_read_b128 v[136:139], v152 offset:0
	ds_read_b128 v[140:143], v152 offset:0x1000
	v_mov_b32_e32 v128, 0
	v_mov_b32_e32 v129, 0
	v_mov_b32_e32 v130, 0
	v_mov_b32_e32 v131, 0
	v_mov_b32_e32 v132, 0
	v_mov_b32_e32 v133, 0
	v_mov_b32_e32 v134, 0
	v_mov_b32_e32 v135, 0
	s_add_i32 s90, s90, 1
	s_branch .Lattn_exp_done_0_1

; #define SCHED() __builtin_amdgcn_sched_barrier(0)
; #define DSR(dst, addr, off) asm volatile("ds_read_b128 %0, %1 offset:%2" : "=&v"(dst) : "v"(addr), "n"(off) : "memory")
; #define LGKM(n) asm volatile("s_waitcnt lgkmcnt(%0)" ::"n"(n) : "memory")
; #define DSR(dst, addr, off) asm volatile("ds_read_b128 %0, %1 offset:%2" : "=&v"(dst) : "v"(addr), "n"(off) : "memory")
; #define LGKM(n) asm volatile("s_waitcnt lgkmcnt(%0)" ::"n"(n) : "memory")
; __device__ __forceinline__ void attn_phase(char* shm, const Params& p, const u16* __restrict__ qb, const u16* __restrict__ kb,
;                                            const u16* __restrict__ vT, u16* __restrict__ attn) {
;     ...
;         const float df = (float)(kt * 64 + u * 32 + 4 * hh - qpos);
;         bf16x8 P[2][2];
;         bf16x8 kf[2], qf[2];
;         DSR(kf[0], kb_ + kL0, u * 8192); DSR(qf[0], qaddr, 0);
; #pragma unroll
;         for (int c = 0; c < 2; ++c) {
;           f32x16 Sx;
; #pragma unroll
;           for (int i = 0; i < 16; ++i) Sx[i] = -sl2 * fabsf(df + (float)((i & 3) + 8 * (i >> 2)));
; #pragma unroll
;           for (int ks = 0; ks < 4; ++ks) {
;             const int f = c * 4 + ks;
;             if (f < 7) {
;               DSR(kf[(f + 1) & 1], kb_ + (kL0 ^ ((((f + 1) >> 2) * 8 + ((f + 1) & 3) * 2) << 4)), u * 8192);
;               DSR(qf[(f + 1) & 1], qaddr, (f + 1) * 1024);
;               LGKM(2);
;             } else LGKM(0);
;             SCHED();
;             Sx = __builtin_amdgcn_mfma_f32_32x32x16_bf16(kf[f & 1], qf[f & 1], Sx, 0, 0, 0);
;             SCHED();
;           }
;           float pv[16];
; #pragma unroll
;           for (int i = 0; i < 16; ++i) { pv[i] = __builtin_amdgcn_exp2f(Sx[i]); lsum[c] += pv[i]; }
.Lattn_pv_zero_0:
	s_waitcnt lgkmcnt(0)
	v_add_u32_e32 v128, 32, v205
	v_cvt_f32_i32_e32 v128, v128
	ds_read_b128 v[206:209], v160 offset:0x2000
	ds_read_b128 v[210:213], v185 offset:0
	ds_read_b128 v[218:221], v214 offset:0x2000
	ds_read_b128 v[222:225], v185 offset:0x400
	ds_read_b128 v[242:245], v215 offset:0x2000
	ds_read_b128 v[246:249], v185 offset:0x800
	v_add_f32_e32 v129, 1.0, v128
	v_add_f32_e64 v130, v128, s12
	v_add_f32_e64 v131, v128, s13
	v_add_f32_e64 v132, v128, s14
	v_add_f32_e64 v133, v128, s15
	v_add_f32_e64 v134, v128, s20
	v_add_f32_e64 v135, v128, s21
	v_add_f32_e64 v136, v128, s22
	v_add_f32_e64 v137, v128, s23
	v_add_f32_e64 v138, v128, s24
	v_add_f32_e64 v139, v128, s25
	v_add_f32_e64 v140, v128, s26
	v_add_f32_e64 v141, v128, s27
	v_add_f32_e64 v142, v128, s28
	v_add_f32_e64 v143, v128, s29
	v_mul_f32_e64 v142, v178, |v142|
	v_mul_f32_e64 v143, v179, |v143|
	v_mul_f32_e64 v140, v178, |v140|
	v_mul_f32_e64 v141, v179, |v141|
	v_mul_f32_e64 v138, v178, |v138|
	v_mul_f32_e64 v139, v179, |v139|
	v_mul_f32_e64 v136, v178, |v136|
	v_mul_f32_e64 v137, v179, |v137|
	v_mul_f32_e64 v134, v178, |v134|
	v_mul_f32_e64 v135, v179, |v135|
	v_mul_f32_e64 v132, v178, |v132|
	v_mul_f32_e64 v133, v179, |v133|
	v_mul_f32_e64 v130, v178, |v130|
	v_mul_f32_e64 v131, v179, |v131|
	v_mul_f32_e64 v128, v170, |v128|
	v_mul_f32_e64 v129, v171, |v129|
	s_nop 1
	s_waitcnt lgkmcnt(4)
	v_readfirstlane_b32 s88, v128
	s_cmp_gt_u32 s88, 0xc35c0000
	s_cselect_b32 s89, 1, 0
	s_mov_b32 s90, 0
	v_mfma_f32_32x32x16_bf16 v[144:159], v[206:209], v[210:213], v[128:143]
	ds_read_b128 v[206:209], v226 offset:0x2000
	ds_read_b128 v[210:213], v185 offset:0xc00
	s_waitcnt lgkmcnt(4)
	v_mfma_f32_32x32x16_bf16 v[144:159], v[218:221], v[222:225], v[144:159]
	ds_read_b128 v[218:221], v227 offset:0x2000
	ds_read_b128 v[222:225], v185 offset:0x1000
	s_waitcnt lgkmcnt(4)
	v_mfma_f32_32x32x16_bf16 v[144:159], v[242:245], v[246:249], v[144:159]
	ds_read_b128 v[242:245], v229 offset:0x2000
	ds_read_b128 v[246:249], v185 offset:0x1400
	s_waitcnt lgkmcnt(4)
	v_mfma_f32_32x32x16_bf16 v[144:159], v[206:209], v[210:213], v[144:159]
	ds_read_b128 v[206:209], v230 offset:0x2000
	ds_read_b128 v[210:213], v185 offset:0x1800
	s_waitcnt lgkmcnt(4)
	v_mfma_f32_32x32x16_bf16 v[128:143], v[218:221], v[222:225], v[128:143]
	ds_read_b128 v[218:221], v232 offset:0x2000
	ds_read_b128 v[222:225], v185 offset:0x1c00
	s_waitcnt lgkmcnt(4)
	v_mfma_f32_32x32x16_bf16 v[128:143], v[242:245], v[246:249], v[128:143]
	s_waitcnt lgkmcnt(2)
	v_mfma_f32_32x32x16_bf16 v[128:143], v[206:209], v[210:213], v[128:143]
	s_waitcnt lgkmcnt(0)
	v_mfma_f32_32x32x16_bf16 v[128:143], v[218:221], v[222:225], v[128:143]
	s_nop 3
	s_cmp_eq_u32 s89, 0
	s_cbranch_scc1 .Lattn_exp_normal_1_0
	v_max3_f32 v240, v144, v145, v146
	v_max3_f32 v240, v240, v147, v148
	v_max3_f32 v240, v240, v149, v150
	v_max3_f32 v240, v240, v151, v152
	v_max3_f32 v240, v240, v153, v154
	v_max3_f32 v240, v240, v155, v156
	v_max3_f32 v240, v240, v157, v158
	v_max_f32_e32 v240, v240, v159
	v_cmp_ngt_f32_e32 vcc, 0xc3180000, v240
	s_and_b64 vcc, exec, vcc
	s_cbranch_vccnz .Lattn_exp_normal_1_0
	v_mov_b32_e32 v144, 0
	v_mov_b32_e32 v145, 0
	v_mov_b32_e32 v146, 0
	v_mov_b32_e32 v147, 0
	v_mov_b32_e32 v148, 0
	v_mov_b32_e32 v149, 0
	v_mov_b32_e32 v150, 0
	v_mov_b32_e32 v151, 0
	s_add_i32 s90, s90, 1
	s_branch .Lattn_exp_done_1_0

; #define DSR(dst, addr, off) asm volatile("ds_read_b128 %0, %1 offset:%2" : "=&v"(dst) : "v"(addr), "n"(off) : "memory")
; #define DSR(dst, addr, off) asm volatile("ds_read_b128 %0, %1 offset:%2" : "=&v"(dst) : "v"(addr), "n"(off) : "memory")
; __device__ __forceinline__ void attn_phase(char* shm, const Params& p, const u16* __restrict__ qb, const u16* __restrict__ kb,
;                                            const u16* __restrict__ vT, u16* __restrict__ attn) {
;     ...
;           float pv[16];
; #pragma unroll
;           for (int i = 0; i < 16; ++i) { pv[i] = __builtin_amdgcn_exp2f(Sx[i]); lsum[c] += pv[i]; }
; #pragma unroll
;           for (int a = 0; a < 2; ++a) {
;             i32x4 t4;
; #pragma unroll
;             for (int i = 0; i < 4; ++i) t4[i] = pk_bf16(pv[a * 8 + 2 * i], pv[a * 8 + 2 * i + 1]);
;             P[c][a] = __builtin_bit_cast(bf16x8, t4);
;           }
;         }
;         bf16x8 vf[2];
;         DSR(vf[0], vb_ + (vM0 ^ ((u * 4) << 4)), 0);
.Lattn_exp_done_1_0:
	s_nop 3
	s_cmp_eq_u32 s89, 0
	s_cbranch_scc1 .Lattn_exp_normal_1_1
	v_max3_f32 v240, v128, v129, v130
	v_max3_f32 v240, v240, v131, v132
	v_max3_f32 v240, v240, v133, v134
	v_max3_f32 v240, v240, v135, v136
	v_max3_f32 v240, v240, v137, v138
	v_max3_f32 v240, v240, v139, v140
	v_max3_f32 v240, v240, v141, v142
	v_max_f32_e32 v240, v240, v143
	v_cmp_ngt_f32_e32 vcc, 0xc3180000, v240
	s_and_b64 vcc, exec, vcc
	s_cbranch_vccnz .Lattn_exp_normal_1_1
	v_add_u32_e32 v152, s0, v198
	ds_read_b128 v[136:139], v152 offset:0
	ds_read_b128 v[140:143], v152 offset:0x1000
	v_mov_b32_e32 v128, 0
	v_mov_b32_e32 v129, 0
	v_mov_b32_e32 v130, 0
	v_mov_b32_e32 v131, 0
	v_mov_b32_e32 v132, 0
	v_mov_b32_e32 v133, 0
	v_mov_b32_e32 v134, 0
	v_mov_b32_e32 v135, 0
	s_add_i32 s90, s90, 1
	s_branch .Lattn_exp_done_1_1
